# kernel prologue: the four serial kernarg s_loads issued together at entry
# baseline (speedup 1.0000x reference)
; #define ROT() do { sl_prev = sl_cur; sl_cur = sl_next; sl_next = (sl_next == 2 * VSLOT) ? 0 : sl_next + VSLOT; } while (0)
; #define LAS __attribute__((address_space(3)))
; __global__ void __launch_bounds__(NWAVES * 64, 2) mega_fwd(Args args) {
;     extern __shared__ __attribute__((aligned(16))) unsigned char lds[];
;     LAS unsigned char* ldsl = (LAS unsigned char*)lds;
;     volatile LAS unsigned* MISC = (volatile LAS unsigned*)(ldsl + MISC_OFF);
;     const int tid = threadIdx.x, lane = tid & 63, wave = __builtin_amdgcn_readfirstlane(tid >> 6);
;     const int G = gridDim.x; int vcu; { const int bx = blockIdx.x; vcu = (G % 8 == 0) ? (bx % 8) * (G / 8) + bx / 8 : bx; }
;     unsigned char* ws = args.ws;
;     gu32* ctl = (gu32*)(ws + WS_CTL);
;     const float* x = args.in[0]; const float* g_mix = args.in[1]; const float* w_in = args.in[2];
;     const float* lq1 = args.in[3]; const float* lk1 = args.in[4]; const float* lq2 = args.in[5]; const float* lk2 = args.in[6];
;     const float* subg = args.in[7]; const float* relb = args.in[8]; const float* w_out = args.in[9]; const float* g_mlp = args.in[10];
;     const float* w_up = args.in[11]; const float* w_dn = args.in[12]; const float* g_fin = args.in[13];
;     float* out = args.out;
;     bf16* PROJ = (bf16*)(ws + WS_PROJ); bf16* KBI = (bf16*)(ws + WS_KB); bf16* VBI = (bf16*)(ws + WS_VB); bf16* X1B = (bf16*)(ws + WS_X1B); bf16* UB = (bf16*)(ws + WS_U); bf16* XN = (bf16*)(ws + WS_XN); bf16* MIX = (bf16*)(ws + WS_MIX);
;     bf16* WIN = (bf16*)(ws + WS_WIN); bf16* WOUT = (bf16*)(ws + WS_WOUT); bf16* WUP = (bf16*)(ws + WS_WUP); bf16* WDN = (bf16*)(ws + WS_WDN);
;     f32x2* ROT = (f32x2*)(ws + WS_ROT);
;     float* SSQ0 = (float*)(ws + WS_CTL + CTL_SSQ0); float* SSQ1 = (float*)(ws + WS_CTL + CTL_SSQ1); float* SSQ2 = (float*)(ws + WS_CTL + CTL_SSQ2);
;     for (int u = tid; u < (LDS_BYTES - LDSCTL_OFF) / 4; u += NWAVES * 64) ((LAS unsigned*)(ldsl + LDSCTL_OFF))[u] = 0u;
;     __syncthreads();
;     XcdBarrier bar; bar.bar = (unsigned*)(ctl + CW_BAR); bar.x = 0; bar.st = nullptr;
;     if (N_LAUNCHES != PER_PHASE) bar = xcd_barrier_post((unsigned*)(ctl + CW_BAR), MISC + 8);
;     if (N_LAUNCHES != PER_PHASE && G == 256 && tid == 0) { (void)xb_add((unsigned*)(ctl + CW_GRP + 64 * (vcu >> 3) + 1), XB_CENSUS(bar.x)); (void)xb_add((unsigned*)(ctl + CW_TEAM + 64 * (vcu >> 5) + 1), XB_CENSUS(bar.x)); }
_Z8mega_fwd4Args:
	s_load_dword s33, s[0:1], 0x88
	s_load_dwordx16 s[56:71], s[0:1], 0x40
	s_load_dwordx2 s[98:99], s[0:1], 0x80
	s_load_dwordx16 s[80:95], s[0:1], 0x0
	s_add_u32 s4, s0, 0x88
	s_addc_u32 s5, s1, 0
	v_readfirstlane_b32 s24, v0
	v_writelane_b32 v242, s4, 0
	s_waitcnt lgkmcnt(0)
	s_and_b32 s3, s33, 7
	s_cmp_lg_u32 s3, 0
	s_mov_b32 s76, s2
	v_writelane_b32 v242, s5, 1
	s_cbranch_scc1 .LBB0_2
	s_ashr_i32 s4, s2, 31
	s_lshr_b32 s4, s4, 29
	s_add_i32 s4, s2, s4
	s_and_b32 s5, s4, -8
	s_ashr_i32 s3, s33, 3
	s_sub_i32 s5, s2, s5
	s_mul_i32 s3, s3, s5
	s_ashr_i32 s4, s4, 3
	s_add_i32 s76, s3, s4
.LBB0_2:
	s_movk_i32 s3, 0x200
	v_cmp_gt_u32_e32 vcc, s3, v0
	s_and_saveexec_b64 s[4:5], vcc
	v_lshl_add_u32 v1, v0, 2, 0
	v_add_u32_e32 v1, 0x26800, v1
	v_mov_b32_e32 v2, 0
	ds_write_b32 v1, v2
	s_or_b64 exec, exec, s[4:5]
	s_waitcnt lgkmcnt(0)
	s_add_u32 s4, s70, 0xe004000
	s_barrier
	s_addc_u32 s5, s71, 0
	s_getreg_b32 s3, hwreg(HW_REG_XCC_ID, 0, 4)
	v_writelane_b32 v242, s4, 2
	s_and_b32 s14, s3, 15
	v_cmp_eq_u32_e64 s[6:7], 0, v0
	v_writelane_b32 v242, s5, 3
	s_mov_b64 s[4:5], exec
	v_writelane_b32 v242, s6, 4
	s_nop 1
	v_writelane_b32 v242, s7, 5
	s_and_b64 s[6:7], s[4:5], s[6:7]
	s_mov_b64 exec, s[6:7]
	s_cbranch_execz .LBB0_7
	s_mov_b64 s[6:7], exec
	v_mbcnt_lo_u32_b32 v1, s6, 0
	v_mbcnt_hi_u32_b32 v1, s7, v1
	v_cmp_eq_u32_e32 vcc, 0, v1
	s_and_b64 s[8:9], exec, vcc
	s_mov_b64 exec, s[8:9]
	s_cbranch_execz .LBB0_7
	s_bcnt1_i32_b64 s6, s[6:7]
	s_lshl_b32 s3, s14, 8
	v_mov_b32_e32 v2, s6
	v_readlane_b32 s6, v242, 2
	v_mov_b32_e32 v1, s3
	v_readlane_b32 s7, v242, 3
	s_nop 4
	global_atomic_add v1, v2, s[6:7] offset:1024
.LBB0_7:
	s_or_b64 exec, exec, s[4:5]
	s_mov_b64 s[4:5], s[98:99]
	s_add_u32 s12, s70, 0xe000000
	s_addc_u32 s13, s71, 0
	s_cmpk_eq_i32 s33, 0x100
	s_cselect_b64 s[16:17], -1, 0
	s_waitcnt lgkmcnt(0)
	v_writelane_b32 v242, s4, 6
	s_cmpk_lg_i32 s33, 0x100
	s_nop 0
	v_writelane_b32 v242, s5, 7
	s_cselect_b64 s[4:5], -1, 0
	v_writelane_b32 v242, s4, 8
	s_nop 1
	v_writelane_b32 v242, s5, 9
	s_nop 0
	v_readlane_b32 s4, v242, 4
	v_readlane_b32 s5, v242, 5
	s_and_b64 s[6:7], s[4:5], s[16:17]
	s_mov_b64 s[4:5], exec
	v_writelane_b32 v242, s6, 10
	s_nop 1
	v_writelane_b32 v242, s7, 11
	s_and_b64 s[6:7], s[4:5], s[6:7]
	s_mov_b64 exec, s[6:7]
	s_cbranch_execz .LBB0_12
	s_mov_b64 s[6:7], exec
	s_lshl_b32 s3, s14, 18
	s_bitset1_b32 s3, 8
	v_mbcnt_lo_u32_b32 v1, s6, 0
	s_mul_i32 s3, s3, s14
	v_mbcnt_hi_u32_b32 v1, s7, v1
	s_or_b32 s3, s3, 1
	v_cmp_eq_u32_e32 vcc, 0, v1
	s_and_saveexec_b64 s[8:9], vcc
	s_cbranch_execz .LBB0_10
	s_lshl_b32 s10, s76, 3
	s_andn2_b32 s10, s10, 63
	s_ashr_i32 s11, s10, 31
	s_lshl_b64 s[10:11], s[10:11], 2
	s_add_u32 s10, s12, s10
	s_addc_u32 s11, s13, s11
	s_bcnt1_i32_b64 s6, s[6:7]
	s_mul_i32 s6, s3, s6
	v_mov_b32_e32 v1, 0x18000
	v_mov_b32_e32 v2, s6
	global_atomic_add v1, v2, s[10:11] offset:4

; #define LAS __attribute__((address_space(3)))
; __global__ void __launch_bounds__(NWAVES * 64, 2) mega_fwd(Args args) {
;     ...
;     bf16* PROJ = (bf16*)(ws + WS_PROJ); bf16* KBI = (bf16*)(ws + WS_KB); bf16* VBI = (bf16*)(ws + WS_VB); bf16* X1B = (bf16*)(ws + WS_X1B); bf16* UB = (bf16*)(ws + WS_U); bf16* XN = (bf16*)(ws + WS_XN); bf16* MIX = (bf16*)(ws + WS_MIX);
;     bf16* WIN = (bf16*)(ws + WS_WIN); bf16* WOUT = (bf16*)(ws + WS_WOUT); bf16* WUP = (bf16*)(ws + WS_WUP); bf16* WDN = (bf16*)(ws + WS_WDN);
;     f32x2* ROT = (f32x2*)(ws + WS_ROT);
;     float* SSQ0 = (float*)(ws + WS_CTL + CTL_SSQ0); float* SSQ1 = (float*)(ws + WS_CTL + CTL_SSQ1); float* SSQ2 = (float*)(ws + WS_CTL + CTL_SSQ2);
;     for (int u = tid; u < (LDS_BYTES - LDSCTL_OFF) / 4; u += NWAVES * 64) ((LAS unsigned*)(ldsl + LDSCTL_OFF))[u] = 0u;
;     __syncthreads();
;     XcdBarrier bar; bar.bar = (unsigned*)(ctl + CW_BAR); bar.x = 0; bar.st = nullptr;
;     if (N_LAUNCHES != PER_PHASE) bar = xcd_barrier_post((unsigned*)(ctl + CW_BAR), MISC + 8);
;     if (N_LAUNCHES != PER_PHASE && G == 256 && tid == 0) { (void)xb_add((unsigned*)(ctl + CW_GRP + 64 * (vcu >> 3) + 1), XB_CENSUS(bar.x)); (void)xb_add((unsigned*)(ctl + CW_TEAM + 64 * (vcu >> 5) + 1), XB_CENSUS(bar.x)); }
;     ...
;     unsigned gtarget = 0;
;     const bool PANEL_NOINV = ((vcu >> 3) != 21) && ((vcu >> 3) != 31);
;     ...
;     const int lo = args.ph_lo, hi = args.ph_hi;
;     ...
;     if (IN(0)) {
;         LAS float* scr = (LAS float*)(ldsl + RING_OFF + wave * 16896);
;         const int gw = vcu * NWAVES + wave, NGW = G * NWAVES;
;         constexpr int I_IN = (DM / 64) * (NIN / 64), I_OUT = (DM / 64) * (DM / 64), I_UP = (DM / 64) * (DFF / 64), I_DN = (DFF / 64) * (DM / 64);
;         const int NITEMS = (G == 256) ? I_IN : I_IN + I_OUT + I_UP + I_DN;
;         auto mk = [&](int it) -> TItem {
;             int r = it;
;             if (r < I_IN) return TItem{w_in, g_mix, WIN, DM, NIN, r, true}; r -= I_IN;
;             if (r < I_OUT) return TItem{w_out, nullptr, WOUT, DM, DM, r, false}; r -= I_OUT;
;             if (r < I_UP) return TItem{w_up, g_mlp, WUP, DM, DFF, r, false}; r -= I_UP;
;             return TItem{w_dn, nullptr, WDN, DFF, DM, r, false};
;         };
;         {
;             f32x4 va[16], vb[16]; int it = gw;
;             if (it < NITEMS) p0_load(mk(it), lane, va);
.LBB0_12:
	v_writelane_b32 v242, s16, 12
	s_nop 1
	v_writelane_b32 v242, s17, 13
	v_writelane_b32 v242, s2, 14
	v_writelane_b32 v242, s14, 15
	v_writelane_b32 v242, s12, 16
	s_nop 1
	v_writelane_b32 v242, s13, 17
	s_or_b64 exec, exec, s[4:5]
	s_mov_b64 s[8:9], s[80:81]
	s_mov_b64 s[10:11], s[82:83]
	s_mov_b64 s[12:13], s[84:85]
	s_mov_b64 s[14:15], s[86:87]
	s_mov_b64 s[16:17], s[88:89]
	s_mov_b64 s[18:19], s[90:91]
	s_mov_b64 s[20:21], s[92:93]
	s_mov_b64 s[22:23], s[94:95]
	s_add_u32 s90, s70, 0x6000000
	s_addc_u32 s91, s71, 0
	s_add_u32 s92, s70, 0x8000000
	s_addc_u32 s93, s71, 0
	s_add_u32 s94, s70, 0xe200000
	s_addc_u32 s95, s71, 0
	s_add_u32 s84, s70, 0xa000000
	s_addc_u32 s85, s71, 0
	s_add_u32 s74, s70, 0xc000000
	s_addc_u32 s75, s71, 0
	s_lshr_b32 s0, s24, 6
	v_writelane_b32 v242, s0, 18
	v_and_b32_e32 v194, 63, v0
	v_readlane_b32 s4, v242, 6
	v_readlane_b32 s5, v242, 7
	s_cmp_lt_i32 s4, 1
	s_cselect_b64 s[0:1], -1, 0
	s_cmp_gt_i32 s5, 0
	s_cselect_b64 s[2:3], -1, 0
	s_and_b64 s[0:1], s[0:1], s[2:3]
	s_andn2_b64 vcc, exec, s[0:1]
	s_cbranch_vccnz .LBB0_155
	s_lshl_b32 s0, s76, 3
	v_readlane_b32 s1, v242, 18
	s_add_i32 s6, s0, s1
	v_readlane_b32 s0, v242, 12
	v_readlane_b32 s1, v242, 13
	s_movk_i32 s2, 0xc00
	s_and_b64 s[0:1], s[0:1], exec
	s_cselect_b32 s3, s2, 0x3000
	s_cmp_lt_i32 s6, s3
	s_cselect_b64 s[0:1], -1, 0
	s_cmp_ge_i32 s6, s3
	s_cbranch_scc1 .LBB0_26
	s_cmpk_lt_i32 s6, 0xc00
	s_cbranch_scc1 .LBB0_18
	s_cmpk_gt_u32 s6, 0xfff
	s_cbranch_scc0 .LBB0_19
	s_cmpk_gt_u32 s6, 0x1fff
	s_cbranch_scc0 .LBB0_20
	s_add_i32 s2, s6, 0xffffe000
	s_mov_b64 s[24:25], 0
	s_mov_b64 s[4:5], s[64:65]
	s_branch .LBB0_21
